# v27: + SB tile counter / first-tile flag moved from VALU+readfirstlane to SALU
# speedup vs baseline: 1.0031x; 1.0031x over previous
; #define LAS __attribute__((address_space(3)))
; #define MFMA32(a, b, c) __builtin_amdgcn_mfma_f32_32x32x16_bf16((a), (b), (c), 0, 0, 0)
; template <int MODE>
; DI bool attn_tile(const bf16x8 (&kf)[4], const bf16x8 (&vf)[4], const bf16x8 (&qf)[4], int key0, int q0, int tq, int hi, int x32, int own, unsigned selmask,
;                   float& m_run, float& l_run, f32x16& O0, f32x16& O1) {
;     f32x16 s = zero16();
; #pragma unroll
;     for (int kk = 0; kk < 4; ++kk) s = MFMA32(kf[kk], qf[kk], s);
;     if constexpr (MODE == 0) {
;         float lk[16];
;         if (key0 == q0) {
; #pragma unroll
;             for (int i = 0; i < 16; ++i) {
;                 const int key = key0 + 16 * (i >> 3) + 8 * hi + (i & 7);
;                 const bool past = key < tq;
;                 const float z = s[i] * SC2;
;                 const float l1 = __builtin_amdgcn_logf(1.f + __builtin_amdgcn_exp2f(-fabsf(z)));
;                 s[i] = past ? (fminf(z, 0.f) - l1) : -INFINITY;
;                 lk[i] = past ? -(fmaxf(z, 0.f) + l1) : 0.f;
;             }
;         } else {
; #pragma unroll
;             for (int i = 0; i < 16; ++i) {
;                 const float z = s[i] * SC2;
;                 const float l1 = __builtin_amdgcn_logf(1.f + __builtin_amdgcn_exp2f(-fabsf(z)));
;                 s[i] = fminf(z, 0.f) - l1; lk[i] = -(fmaxf(z, 0.f) + l1);
;             }
; DI void sb_wg_phase(const bf16* qb, const unsigned char* kfb, const unsigned char* vfb, bf16* ob, int G, LAS unsigned char* lds, const int wave_s) {
;     ...
;         for (int t = qc; t >= 0; --t) {
;             bf16x8 kf[4], vf[4];
;             if (t >= tlo) { const LAS unsigned char* sl = lds + (unsigned)(t & 15) * 8192u + lofs;
;                 kf[0] = *(const LAS bf16x8*)(sl); kf[1] = *(const LAS bf16x8*)(sl + 1024); kf[2] = *(const LAS bf16x8*)(sl + 2048); kf[3] = *(const LAS bf16x8*)(sl + 3072);
;                 vf[0] = *(const LAS bf16x8*)(sl + 4096); vf[1] = *(const LAS bf16x8*)(sl + 5120); vf[2] = *(const LAS bf16x8*)(sl + 6144); vf[3] = *(const LAS bf16x8*)(sl + 7168); }
;             else { const char* kb_ = (const char*)kfb + hbase + ((size_t)t << 12) + lofs; const char* vb_ = (const char*)vfb + hbase + ((size_t)t << 12) + lofs;
;                 kf[0] = *(const bf16x8*)(kb_); kf[1] = *(const bf16x8*)(kb_ + 1024); kf[2] = *(const bf16x8*)(kb_ + 2048); kf[3] = *(const bf16x8*)(kb_ + 3072);
.LBB0_533:
	s_waitcnt vmcnt(0) lgkmcnt(0)
	v_mfma_f32_32x32x16_bf16 v[34:49], v[34:37], v[82:85], 0
	s_mov_b64 s[46:47], -1
	v_mfma_f32_32x32x16_bf16 v[34:49], v[54:57], v[86:89], v[34:49]
	v_mfma_f32_32x32x16_bf16 v[34:49], v[50:53], v[90:93], v[34:49]
	s_sub_u32 s96, s96, 1
	s_cselect_b64 s[80:81], -1, 0
	s_and_b64 vcc, exec, s[80:81]
	v_mfma_f32_32x32x16_bf16 v[34:49], v[58:61], v[94:97], v[34:49]
	s_nop 11
	v_mul_f32_e32 v66, 0x3e38aa3b, v39
	v_mul_f32_e32 v67, 0x3e38aa3b, v40
	v_exp_f32_e64 v65, -|v66|
	v_exp_f32_e64 v68, -|v67|
	v_mul_f32_e32 v63, 0x3e38aa3b, v38
	v_exp_f32_e64 v62, -|v63|
	v_min_f32_e32 v64, 0, v63
	v_max_f32_e32 v124, 0, v63
	v_add_f32_e32 v63, 1.0, v65
	v_min_f32_e32 v65, 0, v66
	v_max_f32_e32 v125, 0, v66
	v_add_f32_e32 v66, 1.0, v68
	v_mul_f32_e32 v68, 0x3e38aa3b, v41
	v_exp_f32_e64 v69, -|v68|
	v_min_f32_e32 v72, 0, v67
	v_max_f32_e32 v128, 0, v67
	v_mul_f32_e32 v67, 0x3e38aa3b, v42
	v_log_f32_e32 v126, v66
	v_add_f32_e32 v66, 1.0, v69
	v_exp_f32_e64 v69, -|v67|
	v_min_f32_e32 v73, 0, v68
	v_max_f32_e32 v129, 0, v68
	v_mul_f32_e32 v68, 0x3e38aa3b, v43
	v_log_f32_e32 v127, v66
	v_add_f32_e32 v66, 1.0, v69
	v_exp_f32_e64 v69, -|v68|
	v_min_f32_e32 v74, 0, v67
	v_max_f32_e32 v132, 0, v67
	v_mul_f32_e32 v67, 0x3e38aa3b, v44
	v_log_f32_e32 v130, v66
	v_add_f32_e32 v66, 1.0, v69
	v_exp_f32_e64 v69, -|v67|
	v_min_f32_e32 v75, 0, v68
	v_max_f32_e32 v133, 0, v68
	v_mul_f32_e32 v68, 0x3e38aa3b, v45
	v_log_f32_e32 v131, v66
	v_add_f32_e32 v66, 1.0, v69
	v_exp_f32_e64 v69, -|v68|
	v_min_f32_e32 v76, 0, v67
	v_max_f32_e32 v136, 0, v67
	v_mul_f32_e32 v67, 0x3e38aa3b, v46
	v_log_f32_e32 v134, v66
	v_add_f32_e32 v66, 1.0, v69
	v_exp_f32_e64 v69, -|v67|
	v_min_f32_e32 v77, 0, v68
	v_max_f32_e32 v137, 0, v68
	v_mul_f32_e32 v68, 0x3e38aa3b, v47
	v_log_f32_e32 v135, v66
	v_add_f32_e32 v66, 1.0, v69
	v_exp_f32_e64 v69, -|v68|
	v_min_f32_e32 v78, 0, v67
	v_max_f32_e32 v140, 0, v67
	v_mul_f32_e32 v67, 0x3e38aa3b, v48
	v_mul_f32_e32 v51, 0x3e38aa3b, v34
	v_mul_f32_e32 v55, 0x3e38aa3b, v35
	v_mul_f32_e32 v57, 0x3e38aa3b, v36
	v_mul_f32_e32 v61, 0x3e38aa3b, v37
	v_log_f32_e32 v138, v66
	v_add_f32_e32 v66, 1.0, v69
	v_exp_f32_e64 v69, -|v67|
	v_mul_f32_e32 v145, 0x3e38aa3b, v49
	v_exp_f32_e64 v52, -|v51|
	v_exp_f32_e64 v53, -|v55|
	v_exp_f32_e64 v56, -|v57|
	v_exp_f32_e64 v59, -|v61|
	v_min_f32_e32 v79, 0, v68
	v_max_f32_e32 v141, 0, v68
	v_exp_f32_e64 v68, -|v145|
	v_log_f32_e32 v139, v66
	v_add_f32_e32 v66, 1.0, v69
	v_min_f32_e32 v50, 0, v51
	v_add_f32_e32 v52, 1.0, v52
	v_max_f32_e32 v54, 0, v51
	v_add_f32_e32 v51, 1.0, v53
	v_add_f32_e32 v56, 1.0, v56
	v_min_f32_e32 v58, 0, v57
	v_max_f32_e32 v60, 0, v57
	v_add_f32_e32 v57, 1.0, v59
	v_add_f32_e32 v62, 1.0, v62
	v_log_f32_e32 v142, v66
	v_add_f32_e32 v66, 1.0, v68
	v_log_f32_e32 v52, v52
	v_log_f32_e32 v53, v51
	v_log_f32_e32 v56, v56
	v_log_f32_e32 v57, v57
	v_log_f32_e32 v62, v62
	v_log_f32_e32 v63, v63
	v_log_f32_e32 v143, v66
	v_min_f32_e32 v51, 0, v55
	v_max_f32_e32 v55, 0, v55
	v_min_f32_e32 v59, 0, v61
	v_max_f32_e32 v61, 0, v61
	v_max_f32_e32 v144, 0, v67
	v_min_f32_e32 v81, 0, v145
	v_max_f32_e32 v145, 0, v145
	v_min_f32_e32 v80, 0, v67
	v_pk_add_f32 v[66:67], v[50:51], v[52:53] neg_lo:[0,1] neg_hi:[0,1]
	v_pk_add_f32 v[68:69], v[58:59], v[56:57] neg_lo:[0,1] neg_hi:[0,1]
	v_pk_add_f32 v[70:71], v[64:65], v[62:63] neg_lo:[0,1] neg_hi:[0,1]
	v_pk_add_f32 v[50:51], v[54:55], v[52:53] neg_lo:[1,1] neg_hi:[1,1]
	v_pk_add_f32 v[52:53], v[60:61], v[56:57] neg_lo:[1,1] neg_hi:[1,1]
	v_pk_add_f32 v[54:55], v[124:125], v[62:63] neg_lo:[1,1] neg_hi:[1,1]
	v_pk_add_f32 v[56:57], v[128:129], v[126:127] neg_lo:[1,1] neg_hi:[1,1]
	v_pk_add_f32 v[58:59], v[132:133], v[130:131] neg_lo:[1,1] neg_hi:[1,1]
	v_pk_add_f32 v[60:61], v[136:137], v[134:135] neg_lo:[1,1] neg_hi:[1,1]
	v_pk_add_f32 v[62:63], v[140:141], v[138:139] neg_lo:[1,1] neg_hi:[1,1]
	v_pk_add_f32 v[64:65], v[144:145], v[142:143] neg_lo:[1,1] neg_hi:[1,1]
	v_pk_add_f32 v[72:73], v[72:73], v[126:127] neg_lo:[0,1] neg_hi:[0,1]
	v_pk_add_f32 v[74:75], v[74:75], v[130:131] neg_lo:[0,1] neg_hi:[0,1]
	v_pk_add_f32 v[76:77], v[76:77], v[134:135] neg_lo:[0,1] neg_hi:[0,1]
	v_pk_add_f32 v[78:79], v[78:79], v[138:139] neg_lo:[0,1] neg_hi:[0,1]
	v_pk_add_f32 v[80:81], v[80:81], v[142:143] neg_lo:[0,1] neg_hi:[0,1]
	s_mov_b64 s[46:47], 0
